# inproj tail (96 gate channels): 256 half-tiles of 64 tokens so every workgroup takes one, written as the same pipelined stream (6 register stages, 3 LDS buffers)
# speedup vs baseline: 1.0228x; 1.0021x over previous
; #define TASK_LOOP(t, nt, base) for (int t = (int)((blockIdx.x + gridDim.x - ((unsigned)(base) % gridDim.x)) % gridDim.x); t < (nt); t += gridDim.x)
; DI float sigm(float x) { return __builtin_amdgcn_rcpf(1.f + __expf(-x)); }
; template <bool RFA, bool RFB, class LA, class LB, class EPI>
; DI void gemm_tile2s(u16* smem, int nk, LA la, LB lb, EPI epi) {
;     ...
;   ld(ra0, rb0, 0);
;   if (nk > 1) ld(ra1, rb1, 1);
;   stl(ra0, rb0, 0);
;   if (nk > 2) ld(ra0, rb0, 2);
;   __syncthreads();
; DI void phase_inproj_tail(const Prm& p, unsigned char* smem_raw, int l, int& base) {
;   const u16* W = p.WinT + (size_t)l * NWP * 1024;
;   u16* smem = (u16*)smem_raw;
;   TASK_LOOP(t, 128, base) {
;     const int n0 = 8192, m0 = t * 128;
;     auto la = [&](int row, int k) __attribute__((always_inline)) { return *(const u32x4*)(W + (size_t)(n0 + (row & ~31) + perm_m(row & 31)) * 1024 + k); };
;     auto lb = [&](int row, int k) __attribute__((always_inline)) { return *(const u32x4*)(p.hbuf + (size_t)(m0 + row) * 1024 + k); };
;     auto epi = [&](f32x16 (&acc)[2], int wm, int wn, int lane) __attribute__((always_inline)) {
;       const int lr = lane & 31, lh = lane >> 5;
;       const int tok = m0 + wn * 32 + lr;
; #pragma unroll
;       for (int i = 0; i < 2; ++i) {
;         const int nb = n0 + wm * 64 + i * 32;
;         if (nb >= NW) continue;
; #pragma unroll
;         for (int h2 = 0; h2 < 2; ++h2) {
;           u32x4 o;
; #pragma unroll
;           for (int e = 0; e < 4; ++e) o[e] = pack2(sigm(acc[i][8 * h2 + 2 * e]), sigm(acc[i][8 * h2 + 2 * e + 1]));
;           *(u32x4*)(p.zg + (size_t)tok * 4096 + (nb - 4192) + 16 * lh + 8 * h2) = o;
;         }
;       }
;     };
;     gemm_tile2s<false, false>(smem, 16, la, lb, epi);
;   }
;   base += 128;
; }
.LBB0_2108:
	v_readlane_b32 s0, v255, 30
	s_addk_i32 s0, 0x700
	v_readlane_b32 s2, v253, 57
	s_mul_hi_u32 s1, s0, s2
	s_mul_i32 s1, s1, s30
	s_sub_i32 s0, s0, s1
	s_sub_i32 s1, s0, s30
	s_cmp_ge_u32 s0, s30
	s_cselect_b32 s0, s1, s0
	s_sub_i32 s1, s0, s30
	s_cmp_ge_u32 s0, s30
	s_cselect_b32 s0, s1, s0
	v_readlane_b32 s1, v253, 40
	s_sub_i32 s0, s1, s0
	s_mul_hi_u32 s1, s0, s2
	s_mul_i32 s1, s1, s30
	s_sub_i32 s0, s0, s1
	s_sub_i32 s1, s0, s30
	s_cmp_ge_u32 s0, s30
	s_cselect_b32 s0, s1, s0
	s_sub_i32 s1, s0, s30
	s_cmp_ge_u32 s0, s30
	s_cselect_b32 s4, s1, s0
	v_readlane_b32 s6, v255, 19
	v_readlane_b32 s7, v255, 20
	v_readlane_b32 s8, v253, 20
	v_readlane_b32 s9, v253, 21
	v_readlane_b32 s10, v252, 6
	v_readlane_b32 s11, v252, 7
	v_and_b32_e32 v226, 7, v224
	v_lshlrev_b32_e32 v226, 4, v226
	v_lshrrev_b32_e32 v227, 3, v224
	v_and_b32_e32 v228, 0xffffffe3, v227
	v_lshrrev_b32_e32 v229, 1, v227
	v_and_b32_e32 v229, 12, v229
	v_or_b32_e32 v228, v228, v229
	v_lshlrev_b32_e32 v229, 2, v227
	v_and_b32_e32 v229, 16, v229
	v_or_b32_e32 v228, v228, v229
	v_lshl_add_u32 v210, v228, 11, v226
	v_lshl_add_u32 v211, v227, 11, v226
	s_movk_i32 s12, 0x90
	v_mad_u32_u24 v212, v227, s12, v226
	v_add_u32_e32 v213, 0xd800, v212
	v_lshrrev_b32_e32 v226, 1, v224
	v_and_b32_e32 v227, 16, v226
	v_and_b32_e32 v228, 31, v224
	v_lshrrev_b32_e32 v229, 2, v224
	v_and_b32_e32 v229, 0x60, v229
	v_and_b32_e32 v226, 32, v226
	v_or_b32_e32 v226, v226, v228
	v_or_b32_e32 v228, v229, v228
	v_mad_u32_u24 v214, v228, s12, v227
	v_mad_u32_u24 v215, v226, s12, v227
	v_add_u32_e32 v215, 0xd800, v215
	v_or_b32_e32 v229, v229, v227
	v_lshlrev_b32_e32 v229, 1, v229
	v_lshl_add_u32 v216, v226, 13, v229
	s_add_u32 s0, s6, 0x1000000
	s_addc_u32 s1, s7, 0
	s_add_u32 s2, s0, 0x20000
	s_addc_u32 s3, s1, 0
	s_lshl_b32 s12, s4, 17
	s_add_u32 s4, s8, s12
	s_addc_u32 s5, s9, 0
	s_lshl_b32 s12, s12, 2
	s_add_u32 s10, s10, s12
	s_addc_u32 s11, s11, 0
	s_add_u32 s10, s10, 0x1f40
	s_addc_u32 s11, s11, 0
	global_load_dwordx4 v[20:23], v210, s[0:1]
	global_load_dwordx4 v[24:27], v210, s[2:3]
	global_load_dwordx4 v[28:31], v211, s[4:5]
	global_load_dwordx4 v[32:35], v210, s[0:1] offset:128
	global_load_dwordx4 v[36:39], v210, s[2:3] offset:128
	global_load_dwordx4 v[40:43], v211, s[4:5] offset:128
	global_load_dwordx4 v[44:47], v210, s[0:1] offset:256
	global_load_dwordx4 v[48:51], v210, s[2:3] offset:256
	global_load_dwordx4 v[52:55], v211, s[4:5] offset:256
	global_load_dwordx4 v[56:59], v210, s[0:1] offset:384
	global_load_dwordx4 v[60:63], v210, s[2:3] offset:384
	global_load_dwordx4 v[64:67], v211, s[4:5] offset:384
	global_load_dwordx4 v[68:71], v210, s[0:1] offset:512
	global_load_dwordx4 v[72:75], v210, s[2:3] offset:512
	global_load_dwordx4 v[76:79], v211, s[4:5] offset:512
	global_load_dwordx4 v[80:83], v210, s[0:1] offset:640
	global_load_dwordx4 v[84:87], v210, s[2:3] offset:640
	global_load_dwordx4 v[88:91], v211, s[4:5] offset:640
	s_waitcnt vmcnt(12)
	ds_write_b128 v212, v[20:23]
	ds_write_b128 v212, v[24:27] offset:9216
	ds_write_b128 v213, v[28:31]
	ds_write_b128 v212, v[32:35] offset:18432
	ds_write_b128 v212, v[36:39] offset:27648
	ds_write_b128 v213, v[40:43] offset:9216
	global_load_dwordx4 v[20:23], v210, s[0:1] offset:768
	global_load_dwordx4 v[24:27], v210, s[2:3] offset:768
	global_load_dwordx4 v[28:31], v211, s[4:5] offset:768
	global_load_dwordx4 v[32:35], v210, s[0:1] offset:896
	global_load_dwordx4 v[36:39], v210, s[2:3] offset:896
	global_load_dwordx4 v[40:43], v211, s[4:5] offset:896
	s_waitcnt lgkmcnt(0)
	s_barrier
	ds_read_b128 v[130:133], v214
	ds_read_b128 v[134:137], v215
	ds_read_b128 v[138:141], v214 offset:32
	ds_read_b128 v[142:145], v215 offset:32
	s_waitcnt lgkmcnt(0)
	ds_read_b128 v[146:149], v214 offset:64
	ds_read_b128 v[150:153], v215 offset:64
	v_mfma_f32_32x32x16_bf16 v[2:17], v[130:133], v[134:137], 0
	ds_read_b128 v[154:157], v214 offset:96
	ds_read_b128 v[158:161], v215 offset:96
	s_waitcnt vmcnt(15)
	ds_write_b128 v212, v[44:47] offset:36864
	ds_write_b128 v212, v[48:51] offset:46080
	v_mfma_f32_32x32x16_bf16 v[2:17], v[138:141], v[142:145], v[2:17]
	ds_write_b128 v213, v[52:55] offset:18432
	global_load_dwordx4 v[44:47], v210, s[0:1] offset:1024
	global_load_dwordx4 v[48:51], v210, s[2:3] offset:1024
	global_load_dwordx4 v[52:55], v211, s[4:5] offset:1024
	ds_read_b128 v[130:133], v214 offset:18432
	ds_read_b128 v[134:137], v215 offset:9216
	s_waitcnt lgkmcnt(7)
	v_mfma_f32_32x32x16_bf16 v[2:17], v[146:149], v[150:153], v[2:17]
	ds_read_b128 v[138:141], v214 offset:18464
	ds_read_b128 v[142:145], v215 offset:9248
	s_waitcnt lgkmcnt(7)
	v_mfma_f32_32x32x16_bf16 v[2:17], v[154:157], v[158:161], v[2:17]
	s_waitcnt lgkmcnt(0)
	s_barrier
	ds_read_b128 v[146:149], v214 offset:18496
	ds_read_b128 v[150:153], v215 offset:9280
	v_mfma_f32_32x32x16_bf16 v[2:17], v[130:133], v[134:137], v[2:17]
	ds_read_b128 v[154:157], v214 offset:18528
	ds_read_b128 v[158:161], v215 offset:9312
	s_waitcnt vmcnt(15)
	ds_write_b128 v212, v[56:59]
	ds_write_b128 v212, v[60:63] offset:9216
	v_mfma_f32_32x32x16_bf16 v[2:17], v[138:141], v[142:145], v[2:17]
	ds_write_b128 v213, v[64:67]
	global_load_dwordx4 v[56:59], v210, s[0:1] offset:1152
	global_load_dwordx4 v[60:63], v210, s[2:3] offset:1152
	global_load_dwordx4 v[64:67], v211, s[4:5] offset:1152
	ds_read_b128 v[130:133], v214 offset:36864
	ds_read_b128 v[134:137], v215 offset:18432
	s_waitcnt lgkmcnt(7)
	v_mfma_f32_32x32x16_bf16 v[2:17], v[146:149], v[150:153], v[2:17]
	ds_read_b128 v[138:141], v214 offset:36896
	ds_read_b128 v[142:145], v215 offset:18464
	s_waitcnt lgkmcnt(7)
	v_mfma_f32_32x32x16_bf16 v[2:17], v[154:157], v[158:161], v[2:17]
	s_waitcnt lgkmcnt(0)
	s_barrier
; DI f32x16 mfma(bf16x8 a, bf16x8 b, f32x16 c) { return __builtin_amdgcn_mfma_f32_32x32x16_bf16(a, b, c, 0, 0, 0); }
; #define TASK_LOOP(t, nt, base) for (int t = (int)((blockIdx.x + gridDim.x - ((unsigned)(base) % gridDim.x)) % gridDim.x); t < (nt); t += gridDim.x)
; DI float sigm(float x) { return __builtin_amdgcn_rcpf(1.f + __expf(-x)); }
; template <bool RFA, bool RFB, class LA, class LB, class EPI>
; DI void gemm_tile2s(u16* smem, int nk, LA la, LB lb, EPI epi) {
;     ...
;   auto compute = [&](int buf) __attribute__((always_inline)) {
;     const u16* Ab = As + buf * TILE_ELEMS + (wm * 64 + lr) * LDT + lh * 8;
;     const u16* Bb = Bs + buf * TILE_ELEMS + (wn * 32 + lr) * LDT + lh * 8;
; #pragma unroll
;     for (int ks = 0; ks < 4; ++ks) {
;       const bf16x8 a0 = *(const bf16x8*)(Ab + ks * 16);
;       const bf16x8 a1 = *(const bf16x8*)(Ab + 32 * LDT + ks * 16);
;       const bf16x8 b = *(const bf16x8*)(Bb + ks * 16);
;       acc[0] = mfma(a0, b, acc[0]);
;       acc[1] = mfma(a1, b, acc[1]);
;     }
;   };
; DI void phase_inproj_tail(const Prm& p, unsigned char* smem_raw, int l, int& base) {
;   const u16* W = p.WinT + (size_t)l * NWP * 1024;
;   u16* smem = (u16*)smem_raw;
;   TASK_LOOP(t, 128, base) {
;     const int n0 = 8192, m0 = t * 128;
;     auto la = [&](int row, int k) __attribute__((always_inline)) { return *(const u32x4*)(W + (size_t)(n0 + (row & ~31) + perm_m(row & 31)) * 1024 + k); };
;     auto lb = [&](int row, int k) __attribute__((always_inline)) { return *(const u32x4*)(p.hbuf + (size_t)(m0 + row) * 1024 + k); };
;     auto epi = [&](f32x16 (&acc)[2], int wm, int wn, int lane) __attribute__((always_inline)) {
;       const int lr = lane & 31, lh = lane >> 5;
;       const int tok = m0 + wn * 32 + lr;
; #pragma unroll
;       for (int i = 0; i < 2; ++i) {
;         const int nb = n0 + wm * 64 + i * 32;
;         if (nb >= NW) continue;
; #pragma unroll
;         for (int h2 = 0; h2 < 2; ++h2) {
;           u32x4 o;
; #pragma unroll
;           for (int e = 0; e < 4; ++e) o[e] = pack2(sigm(acc[i][8 * h2 + 2 * e]), sigm(acc[i][8 * h2 + 2 * e + 1]));
;           *(u32x4*)(p.zg + (size_t)tok * 4096 + (nb - 4192) + 16 * lh + 8 * h2) = o;
;         }
;       }
;     };
;     gemm_tile2s<false, false>(smem, 16, la, lb, epi);
;   }
;   base += 128;
; }
	ds_read_b128 v[146:149], v214 offset:36928
	ds_read_b128 v[150:153], v215 offset:18496
	v_mfma_f32_32x32x16_bf16 v[2:17], v[130:133], v[134:137], v[2:17]
	ds_read_b128 v[154:157], v214 offset:36960
	ds_read_b128 v[158:161], v215 offset:18528
	s_waitcnt vmcnt(15)
	ds_write_b128 v212, v[68:71] offset:18432
	ds_write_b128 v212, v[72:75] offset:27648
	v_mfma_f32_32x32x16_bf16 v[2:17], v[138:141], v[142:145], v[2:17]
	ds_write_b128 v213, v[76:79] offset:9216
	global_load_dwordx4 v[68:71], v210, s[0:1] offset:1280
	global_load_dwordx4 v[72:75], v210, s[2:3] offset:1280
	global_load_dwordx4 v[76:79], v211, s[4:5] offset:1280
	ds_read_b128 v[130:133], v214
	ds_read_b128 v[134:137], v215
	s_waitcnt lgkmcnt(7)
	v_mfma_f32_32x32x16_bf16 v[2:17], v[146:149], v[150:153], v[2:17]
	ds_read_b128 v[138:141], v214 offset:32
	ds_read_b128 v[142:145], v215 offset:32
	s_waitcnt lgkmcnt(7)
	v_mfma_f32_32x32x16_bf16 v[2:17], v[154:157], v[158:161], v[2:17]
	s_waitcnt lgkmcnt(0)
	s_barrier
	ds_read_b128 v[146:149], v214 offset:64
	ds_read_b128 v[150:153], v215 offset:64
	v_mfma_f32_32x32x16_bf16 v[2:17], v[130:133], v[134:137], v[2:17]
	ds_read_b128 v[154:157], v214 offset:96
	ds_read_b128 v[158:161], v215 offset:96
	s_waitcnt vmcnt(15)
	ds_write_b128 v212, v[80:83] offset:36864
	ds_write_b128 v212, v[84:87] offset:46080
	v_mfma_f32_32x32x16_bf16 v[2:17], v[138:141], v[142:145], v[2:17]
	ds_write_b128 v213, v[88:91] offset:18432
	global_load_dwordx4 v[80:83], v210, s[0:1] offset:1408
	global_load_dwordx4 v[84:87], v210, s[2:3] offset:1408
	global_load_dwordx4 v[88:91], v211, s[4:5] offset:1408
	ds_read_b128 v[130:133], v214 offset:18432
	ds_read_b128 v[134:137], v215 offset:9216
	s_waitcnt lgkmcnt(7)
	v_mfma_f32_32x32x16_bf16 v[2:17], v[146:149], v[150:153], v[2:17]
	ds_read_b128 v[138:141], v214 offset:18464
	ds_read_b128 v[142:145], v215 offset:9248
	s_waitcnt lgkmcnt(7)
	v_mfma_f32_32x32x16_bf16 v[2:17], v[154:157], v[158:161], v[2:17]
	s_waitcnt lgkmcnt(0)
	s_barrier
	ds_read_b128 v[146:149], v214 offset:18496
	ds_read_b128 v[150:153], v215 offset:9280
	v_mfma_f32_32x32x16_bf16 v[2:17], v[130:133], v[134:137], v[2:17]
	ds_read_b128 v[154:157], v214 offset:18528
	ds_read_b128 v[158:161], v215 offset:9312
	s_waitcnt vmcnt(15)
	ds_write_b128 v212, v[20:23]
	ds_write_b128 v212, v[24:27] offset:9216
	v_mfma_f32_32x32x16_bf16 v[2:17], v[138:141], v[142:145], v[2:17]
	ds_write_b128 v213, v[28:31]
	global_load_dwordx4 v[20:23], v210, s[0:1] offset:1536
	global_load_dwordx4 v[24:27], v210, s[2:3] offset:1536
	global_load_dwordx4 v[28:31], v211, s[4:5] offset:1536
	ds_read_b128 v[130:133], v214 offset:36864
	ds_read_b128 v[134:137], v215 offset:18432
	s_waitcnt lgkmcnt(7)
	v_mfma_f32_32x32x16_bf16 v[2:17], v[146:149], v[150:153], v[2:17]
	ds_read_b128 v[138:141], v214 offset:36896
	ds_read_b128 v[142:145], v215 offset:18464
	s_waitcnt lgkmcnt(7)
	v_mfma_f32_32x32x16_bf16 v[2:17], v[154:157], v[158:161], v[2:17]
	s_waitcnt lgkmcnt(0)
	s_barrier
	ds_read_b128 v[146:149], v214 offset:36928
	ds_read_b128 v[150:153], v215 offset:18496
	v_mfma_f32_32x32x16_bf16 v[2:17], v[130:133], v[134:137], v[2:17]
	ds_read_b128 v[154:157], v214 offset:36960
	ds_read_b128 v[158:161], v215 offset:18528
	s_waitcnt vmcnt(15)
	ds_write_b128 v212, v[32:35] offset:18432
	ds_write_b128 v212, v[36:39] offset:27648
	v_mfma_f32_32x32x16_bf16 v[2:17], v[138:141], v[142:145], v[2:17]
	ds_write_b128 v213, v[40:43] offset:9216
	global_load_dwordx4 v[32:35], v210, s[0:1] offset:1664
	global_load_dwordx4 v[36:39], v210, s[2:3] offset:1664
	global_load_dwordx4 v[40:43], v211, s[4:5] offset:1664
	ds_read_b128 v[130:133], v214
	ds_read_b128 v[134:137], v215
	s_waitcnt lgkmcnt(7)
	v_mfma_f32_32x32x16_bf16 v[2:17], v[146:149], v[150:153], v[2:17]
	ds_read_b128 v[138:141], v214 offset:32
	ds_read_b128 v[142:145], v215 offset:32
	s_waitcnt lgkmcnt(7)
	v_mfma_f32_32x32x16_bf16 v[2:17], v[154:157], v[158:161], v[2:17]
	s_waitcnt lgkmcnt(0)
	s_barrier
	ds_read_b128 v[146:149], v214 offset:64
	ds_read_b128 v[150:153], v215 offset:64
	v_mfma_f32_32x32x16_bf16 v[2:17], v[130:133], v[134:137], v[2:17]
	ds_read_b128 v[154:157], v214 offset:96
	ds_read_b128 v[158:161], v215 offset:96
	s_waitcnt vmcnt(15)
	ds_write_b128 v212, v[44:47] offset:36864
	ds_write_b128 v212, v[48:51] offset:46080
	v_mfma_f32_32x32x16_bf16 v[2:17], v[138:141], v[142:145], v[2:17]
	ds_write_b128 v213, v[52:55] offset:18432
	global_load_dwordx4 v[44:47], v210, s[0:1] offset:1792
	global_load_dwordx4 v[48:51], v210, s[2:3] offset:1792
	global_load_dwordx4 v[52:55], v211, s[4:5] offset:1792
	ds_read_b128 v[130:133], v214 offset:18432
	ds_read_b128 v[134:137], v215 offset:9216
	s_waitcnt lgkmcnt(7)
	v_mfma_f32_32x32x16_bf16 v[2:17], v[146:149], v[150:153], v[2:17]
	ds_read_b128 v[138:141], v214 offset:18464
	ds_read_b128 v[142:145], v215 offset:9248
	s_waitcnt lgkmcnt(7)
	v_mfma_f32_32x32x16_bf16 v[2:17], v[154:157], v[158:161], v[2:17]
	s_waitcnt lgkmcnt(0)
	s_barrier
	ds_read_b128 v[146:149], v214 offset:18496
	ds_read_b128 v[150:153], v215 offset:9280
	v_mfma_f32_32x32x16_bf16 v[2:17], v[130:133], v[134:137], v[2:17]
	ds_read_b128 v[154:157], v214 offset:18528
	ds_read_b128 v[158:161], v215 offset:9312
	s_waitcnt vmcnt(15)
	ds_write_b128 v212, v[56:59]
	ds_write_b128 v212, v[60:63] offset:9216
	v_mfma_f32_32x32x16_bf16 v[2:17], v[138:141], v[142:145], v[2:17]
	ds_write_b128 v213, v[64:67]
	global_load_dwordx4 v[56:59], v210, s[0:1] offset:1920
	global_load_dwordx4 v[60:63], v210, s[2:3] offset:1920
	global_load_dwordx4 v[64:67], v211, s[4:5] offset:1920
	ds_read_b128 v[130:133], v214 offset:36864
	ds_read_b128 v[134:137], v215 offset:18432
	s_waitcnt lgkmcnt(7)
	v_mfma_f32_32x32x16_bf16 v[2:17], v[146:149], v[150:153], v[2:17]
	ds_read_b128 v[138:141], v214 offset:36896
	ds_read_b128 v[142:145], v215 offset:18464
	s_waitcnt lgkmcnt(7)
	v_mfma_f32_32x32x16_bf16 v[2:17], v[154:157], v[158:161], v[2:17]
	s_waitcnt lgkmcnt(0)
	s_barrier
; DI f32x16 mfma(bf16x8 a, bf16x8 b, f32x16 c) { return __builtin_amdgcn_mfma_f32_32x32x16_bf16(a, b, c, 0, 0, 0); }
; #define TASK_LOOP(t, nt, base) for (int t = (int)((blockIdx.x + gridDim.x - ((unsigned)(base) % gridDim.x)) % gridDim.x); t < (nt); t += gridDim.x)
; DI float sigm(float x) { return __builtin_amdgcn_rcpf(1.f + __expf(-x)); }
; template <bool RFA, bool RFB, class LA, class LB, class EPI>
; DI void gemm_tile2s(u16* smem, int nk, LA la, LB lb, EPI epi) {
;     ...
;   auto compute = [&](int buf) __attribute__((always_inline)) {
;     const u16* Ab = As + buf * TILE_ELEMS + (wm * 64 + lr) * LDT + lh * 8;
;     const u16* Bb = Bs + buf * TILE_ELEMS + (wn * 32 + lr) * LDT + lh * 8;
; #pragma unroll
;     for (int ks = 0; ks < 4; ++ks) {
;       const bf16x8 a0 = *(const bf16x8*)(Ab + ks * 16);
;       const bf16x8 a1 = *(const bf16x8*)(Ab + 32 * LDT + ks * 16);
;       const bf16x8 b = *(const bf16x8*)(Bb + ks * 16);
;       acc[0] = mfma(a0, b, acc[0]);
;       acc[1] = mfma(a1, b, acc[1]);
;     }
;   };
; DI void phase_inproj_tail(const Prm& p, unsigned char* smem_raw, int l, int& base) {
;   const u16* W = p.WinT + (size_t)l * NWP * 1024;
;   u16* smem = (u16*)smem_raw;
;   TASK_LOOP(t, 128, base) {
;     const int n0 = 8192, m0 = t * 128;
;     auto la = [&](int row, int k) __attribute__((always_inline)) { return *(const u32x4*)(W + (size_t)(n0 + (row & ~31) + perm_m(row & 31)) * 1024 + k); };
;     auto lb = [&](int row, int k) __attribute__((always_inline)) { return *(const u32x4*)(p.hbuf + (size_t)(m0 + row) * 1024 + k); };
;     auto epi = [&](f32x16 (&acc)[2], int wm, int wn, int lane) __attribute__((always_inline)) {
;       const int lr = lane & 31, lh = lane >> 5;
;       const int tok = m0 + wn * 32 + lr;
; #pragma unroll
;       for (int i = 0; i < 2; ++i) {
;         const int nb = n0 + wm * 64 + i * 32;
;         if (nb >= NW) continue;
; #pragma unroll
;         for (int h2 = 0; h2 < 2; ++h2) {
;           u32x4 o;
; #pragma unroll
;           for (int e = 0; e < 4; ++e) o[e] = pack2(sigm(acc[i][8 * h2 + 2 * e]), sigm(acc[i][8 * h2 + 2 * e + 1]));
;           *(u32x4*)(p.zg + (size_t)tok * 4096 + (nb - 4192) + 16 * lh + 8 * h2) = o;
;         }
;       }
;     };
;     gemm_tile2s<false, false>(smem, 16, la, lb, epi);
;   }
;   base += 128;
; }
	ds_read_b128 v[146:149], v214 offset:36928
	ds_read_b128 v[150:153], v215 offset:18496
	v_mfma_f32_32x32x16_bf16 v[2:17], v[130:133], v[134:137], v[2:17]
	ds_read_b128 v[154:157], v214 offset:36960
	ds_read_b128 v[158:161], v215 offset:18528
	s_waitcnt vmcnt(15)
	ds_write_b128 v212, v[68:71] offset:18432
	ds_write_b128 v212, v[72:75] offset:27648
	v_mfma_f32_32x32x16_bf16 v[2:17], v[138:141], v[142:145], v[2:17]
	ds_write_b128 v213, v[76:79] offset:9216
	ds_read_b128 v[130:133], v214
	ds_read_b128 v[134:137], v215
	s_waitcnt lgkmcnt(7)
	v_mfma_f32_32x32x16_bf16 v[2:17], v[146:149], v[150:153], v[2:17]
	ds_read_b128 v[138:141], v214 offset:32
	ds_read_b128 v[142:145], v215 offset:32
	s_waitcnt lgkmcnt(7)
	v_mfma_f32_32x32x16_bf16 v[2:17], v[154:157], v[158:161], v[2:17]
	s_waitcnt lgkmcnt(0)
	s_barrier
	ds_read_b128 v[146:149], v214 offset:64
	ds_read_b128 v[150:153], v215 offset:64
	v_mfma_f32_32x32x16_bf16 v[2:17], v[130:133], v[134:137], v[2:17]
	ds_read_b128 v[154:157], v214 offset:96
	ds_read_b128 v[158:161], v215 offset:96
	s_waitcnt vmcnt(12)
	ds_write_b128 v212, v[80:83] offset:36864
	ds_write_b128 v212, v[84:87] offset:46080
	v_mfma_f32_32x32x16_bf16 v[2:17], v[138:141], v[142:145], v[2:17]
	ds_write_b128 v213, v[88:91] offset:18432
	ds_read_b128 v[130:133], v214 offset:18432
	ds_read_b128 v[134:137], v215 offset:9216
	s_waitcnt lgkmcnt(7)
	v_mfma_f32_32x32x16_bf16 v[2:17], v[146:149], v[150:153], v[2:17]
	ds_read_b128 v[138:141], v214 offset:18464
	ds_read_b128 v[142:145], v215 offset:9248
	s_waitcnt lgkmcnt(7)
	v_mfma_f32_32x32x16_bf16 v[2:17], v[154:157], v[158:161], v[2:17]
	s_waitcnt lgkmcnt(0)
	s_barrier
	ds_read_b128 v[146:149], v214 offset:18496
	ds_read_b128 v[150:153], v215 offset:9280
	v_mfma_f32_32x32x16_bf16 v[2:17], v[130:133], v[134:137], v[2:17]
	ds_read_b128 v[154:157], v214 offset:18528
	ds_read_b128 v[158:161], v215 offset:9312
	s_waitcnt vmcnt(9)
	ds_write_b128 v212, v[20:23]
	ds_write_b128 v212, v[24:27] offset:9216
	v_mfma_f32_32x32x16_bf16 v[2:17], v[138:141], v[142:145], v[2:17]
	ds_write_b128 v213, v[28:31]
	ds_read_b128 v[130:133], v214 offset:36864
	ds_read_b128 v[134:137], v215 offset:18432
	s_waitcnt lgkmcnt(7)
	v_mfma_f32_32x32x16_bf16 v[2:17], v[146:149], v[150:153], v[2:17]
	ds_read_b128 v[138:141], v214 offset:36896
	ds_read_b128 v[142:145], v215 offset:18464
	s_waitcnt lgkmcnt(7)
	v_mfma_f32_32x32x16_bf16 v[2:17], v[154:157], v[158:161], v[2:17]
	s_waitcnt lgkmcnt(0)
	s_barrier
	ds_read_b128 v[146:149], v214 offset:36928
	ds_read_b128 v[150:153], v215 offset:18496
	v_mfma_f32_32x32x16_bf16 v[2:17], v[130:133], v[134:137], v[2:17]
	ds_read_b128 v[154:157], v214 offset:36960
	ds_read_b128 v[158:161], v215 offset:18528
	s_waitcnt vmcnt(6)
	ds_write_b128 v212, v[32:35] offset:18432
	ds_write_b128 v212, v[36:39] offset:27648
	v_mfma_f32_32x32x16_bf16 v[2:17], v[138:141], v[142:145], v[2:17]
	ds_write_b128 v213, v[40:43] offset:9216
	ds_read_b128 v[130:133], v214
	ds_read_b128 v[134:137], v215
	s_waitcnt lgkmcnt(7)
	v_mfma_f32_32x32x16_bf16 v[2:17], v[146:149], v[150:153], v[2:17]
	ds_read_b128 v[138:141], v214 offset:32
	ds_read_b128 v[142:145], v215 offset:32
	s_waitcnt lgkmcnt(7)
	v_mfma_f32_32x32x16_bf16 v[2:17], v[154:157], v[158:161], v[2:17]
	s_waitcnt lgkmcnt(0)
	s_barrier
	ds_read_b128 v[146:149], v214 offset:64
	ds_read_b128 v[150:153], v215 offset:64
	v_mfma_f32_32x32x16_bf16 v[2:17], v[130:133], v[134:137], v[2:17]
	ds_read_b128 v[154:157], v214 offset:96
	ds_read_b128 v[158:161], v215 offset:96
	s_waitcnt vmcnt(3)
	ds_write_b128 v212, v[44:47] offset:36864
	ds_write_b128 v212, v[48:51] offset:46080
	v_mfma_f32_32x32x16_bf16 v[2:17], v[138:141], v[142:145], v[2:17]
	ds_write_b128 v213, v[52:55] offset:18432
	ds_read_b128 v[130:133], v214 offset:18432
	ds_read_b128 v[134:137], v215 offset:9216
	s_waitcnt lgkmcnt(7)
	v_mfma_f32_32x32x16_bf16 v[2:17], v[146:149], v[150:153], v[2:17]
	ds_read_b128 v[138:141], v214 offset:18464
	ds_read_b128 v[142:145], v215 offset:9248
	s_waitcnt lgkmcnt(7)
	v_mfma_f32_32x32x16_bf16 v[2:17], v[154:157], v[158:161], v[2:17]
	s_waitcnt lgkmcnt(0)
	s_barrier
; DI float sigm(float x) { return __builtin_amdgcn_rcpf(1.f + __expf(-x)); }
; DI void phase_inproj_tail(const Prm& p, unsigned char* smem_raw, int l, int& base) {
;     ...
;     auto epi = [&](f32x16 (&acc)[2], int wm, int wn, int lane) __attribute__((always_inline)) {
;       const int lr = lane & 31, lh = lane >> 5;
;       const int tok = m0 + wn * 32 + lr;
; #pragma unroll
;       for (int i = 0; i < 2; ++i) {
;         const int nb = n0 + wm * 64 + i * 32;
;         if (nb >= NW) continue;
; #pragma unroll
;         for (int h2 = 0; h2 < 2; ++h2) {
;           u32x4 o;
; #pragma unroll
;           for (int e = 0; e < 4; ++e) o[e] = pack2(sigm(acc[i][8 * h2 + 2 * e]), sigm(acc[i][8 * h2 + 2 * e + 1]));
;           *(u32x4*)(p.zg + (size_t)tok * 4096 + (nb - 4192) + 16 * lh + 8 * h2) = o;
;         }
;       }
;     };
	ds_read_b128 v[146:149], v214 offset:18496
	ds_read_b128 v[150:153], v215 offset:9280
	v_mfma_f32_32x32x16_bf16 v[2:17], v[130:133], v[134:137], v[2:17]
	ds_read_b128 v[154:157], v214 offset:18528
	ds_read_b128 v[158:161], v215 offset:9312
	s_waitcnt vmcnt(0)
	ds_write_b128 v212, v[56:59]
	ds_write_b128 v212, v[60:63] offset:9216
	v_mfma_f32_32x32x16_bf16 v[2:17], v[138:141], v[142:145], v[2:17]
	ds_write_b128 v213, v[64:67]
	ds_read_b128 v[130:133], v214 offset:36864
	ds_read_b128 v[134:137], v215 offset:18432
	s_waitcnt lgkmcnt(7)
	v_mfma_f32_32x32x16_bf16 v[2:17], v[146:149], v[150:153], v[2:17]
	ds_read_b128 v[138:141], v214 offset:36896
	ds_read_b128 v[142:145], v215 offset:18464
	s_waitcnt lgkmcnt(7)
	v_mfma_f32_32x32x16_bf16 v[2:17], v[154:157], v[158:161], v[2:17]
	s_waitcnt lgkmcnt(0)
	s_barrier
	ds_read_b128 v[146:149], v214 offset:36928
	ds_read_b128 v[150:153], v215 offset:18496
	v_mfma_f32_32x32x16_bf16 v[2:17], v[130:133], v[134:137], v[2:17]
	ds_read_b128 v[154:157], v214 offset:36960
	ds_read_b128 v[158:161], v215 offset:18528
	v_mfma_f32_32x32x16_bf16 v[2:17], v[138:141], v[142:145], v[2:17]
	ds_read_b128 v[130:133], v214
	ds_read_b128 v[134:137], v215
	s_waitcnt lgkmcnt(4)
	v_mfma_f32_32x32x16_bf16 v[2:17], v[146:149], v[150:153], v[2:17]
	ds_read_b128 v[138:141], v214 offset:32
	ds_read_b128 v[142:145], v215 offset:32
	s_waitcnt lgkmcnt(4)
	v_mfma_f32_32x32x16_bf16 v[2:17], v[154:157], v[158:161], v[2:17]
	s_waitcnt lgkmcnt(0)
	s_barrier
	ds_read_b128 v[146:149], v214 offset:64
	ds_read_b128 v[150:153], v215 offset:64
	v_mfma_f32_32x32x16_bf16 v[2:17], v[130:133], v[134:137], v[2:17]
	ds_read_b128 v[154:157], v214 offset:96
	ds_read_b128 v[158:161], v215 offset:96
	v_mfma_f32_32x32x16_bf16 v[2:17], v[138:141], v[142:145], v[2:17]
	s_waitcnt lgkmcnt(2)
	v_mfma_f32_32x32x16_bf16 v[2:17], v[146:149], v[150:153], v[2:17]
	s_waitcnt lgkmcnt(0)
	v_mfma_f32_32x32x16_bf16 v[2:17], v[154:157], v[158:161], v[2:17]
	s_waitcnt lgkmcnt(0)
	s_barrier
	s_nop 15
	v_mul_f32_e32 v2, 0xbfb8aa3b, v2
	v_mul_f32_e32 v3, 0xbfb8aa3b, v3
	v_mul_f32_e32 v4, 0xbfb8aa3b, v4
	v_mul_f32_e32 v5, 0xbfb8aa3b, v5
	v_mul_f32_e32 v6, 0xbfb8aa3b, v6
	v_mul_f32_e32 v7, 0xbfb8aa3b, v7
	v_mul_f32_e32 v8, 0xbfb8aa3b, v8
	v_mul_f32_e32 v9, 0xbfb8aa3b, v9
	v_mul_f32_e32 v10, 0xbfb8aa3b, v10
	v_mul_f32_e32 v11, 0xbfb8aa3b, v11
	v_mul_f32_e32 v12, 0xbfb8aa3b, v12
	v_mul_f32_e32 v13, 0xbfb8aa3b, v13
	v_mul_f32_e32 v14, 0xbfb8aa3b, v14
	v_mul_f32_e32 v15, 0xbfb8aa3b, v15
	v_mul_f32_e32 v16, 0xbfb8aa3b, v16
	v_mul_f32_e32 v17, 0xbfb8aa3b, v17
	v_exp_f32_e32 v2, v2
	v_exp_f32_e32 v3, v3
	v_exp_f32_e32 v4, v4
	v_exp_f32_e32 v5, v5
	v_exp_f32_e32 v6, v6
	v_exp_f32_e32 v7, v7
	v_exp_f32_e32 v8, v8
	v_exp_f32_e32 v9, v9
	v_exp_f32_e32 v10, v10
	v_exp_f32_e32 v11, v11
	v_exp_f32_e32 v12, v12
	v_exp_f32_e32 v13, v13
	v_exp_f32_e32 v14, v14
	v_exp_f32_e32 v15, v15
	v_exp_f32_e32 v16, v16
	v_exp_f32_e32 v17, v17
	v_add_f32_e32 v2, 1.0, v2
	v_add_f32_e32 v3, 1.0, v3
	v_add_f32_e32 v4, 1.0, v4
	v_add_f32_e32 v5, 1.0, v5
	v_add_f32_e32 v6, 1.0, v6
	v_add_f32_e32 v7, 1.0, v7
	v_add_f32_e32 v8, 1.0, v8
	v_add_f32_e32 v9, 1.0, v9
	v_add_f32_e32 v10, 1.0, v10
	v_add_f32_e32 v11, 1.0, v11
	v_add_f32_e32 v12, 1.0, v12
	v_add_f32_e32 v13, 1.0, v13
	v_add_f32_e32 v14, 1.0, v14
	v_add_f32_e32 v15, 1.0, v15
	v_add_f32_e32 v16, 1.0, v16
	v_add_f32_e32 v17, 1.0, v17
	v_rcp_f32_e32 v2, v2
	v_rcp_f32_e32 v3, v3
	v_rcp_f32_e32 v4, v4
	v_rcp_f32_e32 v5, v5
	v_rcp_f32_e32 v6, v6
	v_rcp_f32_e32 v7, v7
	v_rcp_f32_e32 v8, v8
	v_rcp_f32_e32 v9, v9
	v_rcp_f32_e32 v10, v10
	v_rcp_f32_e32 v11, v11
	v_rcp_f32_e32 v12, v12
	v_rcp_f32_e32 v13, v13
	v_rcp_f32_e32 v14, v14
	v_rcp_f32_e32 v15, v15
	v_rcp_f32_e32 v16, v16
	v_rcp_f32_e32 v17, v17
	v_cvt_pk_bf16_f32 v20, v2, v3
	v_cvt_pk_bf16_f32 v21, v4, v5
	v_cvt_pk_bf16_f32 v22, v6, v7
	v_cvt_pk_bf16_f32 v23, v8, v9
	v_cvt_pk_bf16_f32 v24, v10, v11
	v_cvt_pk_bf16_f32 v25, v12, v13
	v_cvt_pk_bf16_f32 v26, v14, v15
	v_cvt_pk_bf16_f32 v27, v16, v17
	v_cmp_gt_u32_e32 vcc, 0x180, v224
	s_and_saveexec_b64 s[12:13], vcc
	global_store_dwordx4 v216, v[20:23], s[10:11]
	global_store_dwordx4 v216, v[24:27], s[10:11] offset:16
	s_or_b64 exec, exec, s[12:13]
